# grid/XCD barrier: waiting (non-leader) workgroups issue their L1 invalidate before spinning instead of after the release; nothing but sc1 polls is loaded in between
# speedup vs baseline: 1.0037x; 1.0027x over previous
.LBB0_210:
	s_lshl_b32 s4, s55, 8
	s_add_u32 s4, s80, s4
	s_addc_u32 s5, s81, 0
	v_mov_b32_e32 v2, 0x1000
	v_mov_b32_e32 v4, 1
	global_atomic_add v4, v2, v4, s[4:5] offset:1024 sc0
	v_cvt_f32_u32_e32 v2, v3
	v_sub_u32_e32 v5, 0, v3
	v_rcp_iflag_f32_e32 v2, v2
	s_nop 0
	v_mul_f32_e32 v2, 0x4f7ffffe, v2
	v_cvt_u32_f32_e32 v2, v2
	v_mul_lo_u32 v5, v5, v2
	v_mul_hi_u32 v5, v2, v5
	v_add_u32_e32 v2, v2, v5
	s_waitcnt vmcnt(0)
	v_mul_hi_u32 v2, v4, v2
	v_mul_lo_u32 v5, v2, v3
	v_sub_u32_e32 v5, v4, v5
	v_add_u32_e32 v6, 1, v2
	v_cmp_ge_u32_e32 vcc, v5, v3
	v_add_u32_e32 v4, 1, v4
	s_nop 0
	v_cndmask_b32_e32 v2, v2, v6, vcc
	v_sub_u32_e32 v6, v5, v3
	v_cndmask_b32_e32 v5, v5, v6, vcc
	v_add_u32_e32 v6, 1, v2
	v_cmp_ge_u32_e32 vcc, v5, v3
	s_nop 1
	v_cndmask_b32_e32 v2, v2, v6, vcc
	v_mul_lo_u32 v5, v3, v2
	v_add_u32_e32 v3, v5, v3
	v_cmp_ne_u32_e32 vcc, v4, v3
	s_and_saveexec_b64 s[6:7], vcc
	s_xor_b64 s[6:7], exec, s[6:7]
	s_cbranch_execz .LBB0_223
	s_waitcnt lgkmcnt(0)
	v_mov_b32_e32 v1, 0x2000
	buffer_inv sc1
	global_load_dword v1, v1, s[4:5] offset:1024 sc1
	s_add_u32 s10, s4, 0x2400
	s_addc_u32 s11, s5, 0
	s_waitcnt vmcnt(0)
	v_cmp_eq_u32_e32 vcc, v1, v2
	s_and_saveexec_b64 s[8:9], vcc
	s_cbranch_execz .LBB0_222
	s_mov_b32 s22, 1
	s_mov_b64 s[12:13], 0
	v_mov_b32_e32 v1, 0
	s_branch .LBB0_214

.LBB0_222:
	s_or_b64 exec, exec, s[8:9]
	s_waitcnt vmcnt(0)
	s_nop 0
	s_waitcnt vmcnt(0)

.LBB0_455:
	v_readlane_b32 s8, v254, 57
	v_readlane_b32 s9, v254, 58
	v_mov_b32_e32 v0, 1
	v_sub_u32_e32 v5, 0, v3
	s_nop 2
	global_atomic_add v4, v1, v0, s[8:9] sc0
	v_cvt_f32_u32_e32 v0, v3
	v_rcp_iflag_f32_e32 v0, v0
	s_nop 0
	v_mul_f32_e32 v0, 0x4f7ffffe, v0
	v_cvt_u32_f32_e32 v0, v0
	v_mul_lo_u32 v5, v5, v0
	v_mul_hi_u32 v5, v0, v5
	v_add_u32_e32 v0, v0, v5
	s_waitcnt vmcnt(0)
	v_mul_hi_u32 v0, v4, v0
	v_mul_lo_u32 v5, v0, v3
	v_sub_u32_e32 v5, v4, v5
	v_add_u32_e32 v6, 1, v0
	v_cmp_ge_u32_e32 vcc, v5, v3
	v_add_u32_e32 v4, 1, v4
	s_nop 0
	v_cndmask_b32_e32 v0, v0, v6, vcc
	v_sub_u32_e32 v6, v5, v3
	v_cndmask_b32_e32 v5, v5, v6, vcc
	v_add_u32_e32 v6, 1, v0
	v_cmp_ge_u32_e32 vcc, v5, v3
	s_nop 1
	v_cndmask_b32_e32 v0, v0, v6, vcc
	v_mul_lo_u32 v5, v3, v0
	v_add_u32_e32 v3, v5, v3
	v_cmp_ne_u32_e32 vcc, v4, v3
	s_and_saveexec_b64 s[8:9], vcc
	s_xor_b64 s[18:19], exec, s[8:9]
	s_cbranch_execz .LBB0_468
	v_readlane_b32 s8, v254, 59
	v_readlane_b32 s9, v254, 60
	s_waitcnt lgkmcnt(0)
	s_nop 3
	buffer_inv sc1
	global_load_dword v2, v1, s[8:9] sc1
	s_waitcnt vmcnt(0)
	v_cmp_eq_u32_e32 vcc, v2, v0
	s_and_saveexec_b64 s[30:31], vcc
	s_cbranch_execz .LBB0_467
	s_mov_b32 s7, 1
	s_mov_b64 s[34:35], 0
	s_branch .LBB0_459

.LBB0_467:
	s_or_b64 exec, exec, s[30:31]
	s_waitcnt vmcnt(0)
	s_nop 0
	s_waitcnt vmcnt(0)

.LBB0_676:
	v_readlane_b32 s4, v254, 57
	v_readlane_b32 s5, v254, 58
	v_mov_b32_e32 v0, 1
	v_sub_u32_e32 v5, 0, v3
	s_nop 2
	global_atomic_add v4, v1, v0, s[4:5] sc0
	v_cvt_f32_u32_e32 v0, v3
	v_rcp_iflag_f32_e32 v0, v0
	s_nop 0
	v_mul_f32_e32 v0, 0x4f7ffffe, v0
	v_cvt_u32_f32_e32 v0, v0
	v_mul_lo_u32 v5, v5, v0
	v_mul_hi_u32 v5, v0, v5
	v_add_u32_e32 v0, v0, v5
	s_waitcnt vmcnt(0)
	v_mul_hi_u32 v0, v4, v0
	v_mul_lo_u32 v5, v0, v3
	v_sub_u32_e32 v5, v4, v5
	v_add_u32_e32 v6, 1, v0
	v_cmp_ge_u32_e32 vcc, v5, v3
	v_add_u32_e32 v4, 1, v4
	s_nop 0
	v_cndmask_b32_e32 v0, v0, v6, vcc
	v_sub_u32_e32 v6, v5, v3
	v_cndmask_b32_e32 v5, v5, v6, vcc
	v_add_u32_e32 v6, 1, v0
	v_cmp_ge_u32_e32 vcc, v5, v3
	s_nop 1
	v_cndmask_b32_e32 v0, v0, v6, vcc
	v_mul_lo_u32 v5, v3, v0
	v_add_u32_e32 v3, v5, v3
	v_cmp_ne_u32_e32 vcc, v4, v3
	s_and_saveexec_b64 s[4:5], vcc
	s_xor_b64 s[4:5], exec, s[4:5]
	s_cbranch_execz .LBB0_689
	v_readlane_b32 s8, v254, 59
	v_readlane_b32 s9, v254, 60
	s_waitcnt lgkmcnt(0)
	s_nop 3
	buffer_inv sc1
	global_load_dword v2, v1, s[8:9] sc1
	s_waitcnt vmcnt(0)
	v_cmp_eq_u32_e32 vcc, v2, v0
	s_and_saveexec_b64 s[18:19], vcc
	s_cbranch_execz .LBB0_688
	s_mov_b32 s1, 1
	s_mov_b64 s[30:31], 0
	s_branch .LBB0_680

.LBB0_688:
	s_or_b64 exec, exec, s[18:19]
	s_waitcnt vmcnt(0)
	s_nop 0
	s_waitcnt vmcnt(0)

.LBB0_1068:
	v_readlane_b32 s4, v254, 57
	v_readlane_b32 s5, v254, 58
	v_mov_b32_e32 v0, 1
	v_sub_u32_e32 v5, 0, v3
	s_nop 2
	global_atomic_add v4, v1, v0, s[4:5] sc0
	v_cvt_f32_u32_e32 v0, v3
	v_rcp_iflag_f32_e32 v0, v0
	s_nop 0
	v_mul_f32_e32 v0, 0x4f7ffffe, v0
	v_cvt_u32_f32_e32 v0, v0
	v_mul_lo_u32 v5, v5, v0
	v_mul_hi_u32 v5, v0, v5
	v_add_u32_e32 v0, v0, v5
	s_waitcnt vmcnt(0)
	v_mul_hi_u32 v0, v4, v0
	v_mul_lo_u32 v5, v0, v3
	v_sub_u32_e32 v5, v4, v5
	v_add_u32_e32 v6, 1, v0
	v_cmp_ge_u32_e32 vcc, v5, v3
	v_add_u32_e32 v4, 1, v4
	s_nop 0
	v_cndmask_b32_e32 v0, v0, v6, vcc
	v_sub_u32_e32 v6, v5, v3
	v_cndmask_b32_e32 v5, v5, v6, vcc
	v_add_u32_e32 v6, 1, v0
	v_cmp_ge_u32_e32 vcc, v5, v3
	s_nop 1
	v_cndmask_b32_e32 v0, v0, v6, vcc
	v_mul_lo_u32 v5, v3, v0
	v_add_u32_e32 v3, v5, v3
	v_cmp_ne_u32_e32 vcc, v4, v3
	s_and_saveexec_b64 s[4:5], vcc
	s_xor_b64 s[4:5], exec, s[4:5]
	s_cbranch_execz .LBB0_1081
	v_readlane_b32 s8, v254, 59
	v_readlane_b32 s9, v254, 60
	s_waitcnt lgkmcnt(0)
	s_nop 3
	buffer_inv sc1
	global_load_dword v2, v1, s[8:9] sc1
	s_waitcnt vmcnt(0)
	v_cmp_eq_u32_e32 vcc, v2, v0
	s_and_saveexec_b64 s[18:19], vcc
	s_cbranch_execz .LBB0_1080
	s_mov_b32 s7, 1
	s_mov_b64 s[30:31], 0
	s_branch .LBB0_1072
